# phase_fin heavy items: z rows for the 32-token block loaded eight at a time (two waits) instead of pairwise (eight waits)
# baseline (speedup 1.0000x reference)
.LBB0_485:
	s_add_i32 s26, s25, s20
	s_ashr_i32 s0, s26, 31
	v_mov_b32_e32 v77, s0
	v_or_b32_e32 v76, s26, v2
	v_mov_b32_e32 v79, s0
	v_or_b32_e32 v78, s26, v4
	v_lshlrev_b64 v[76:77], 11, v[76:77]
	v_lshlrev_b64 v[78:79], 11, v[78:79]
	v_lshl_add_u64 v[76:77], v[66:67], 0, v[76:77]
	s_barrier
	v_lshl_add_u64 v[78:79], v[66:67], 0, v[78:79]
	global_load_dword v214, v[76:77], off
	s_nop 0
	global_load_dword v215, v[78:79], off
	v_mov_b32_e32 v79, s0
	v_or_b32_e32 v78, s26, v6
	v_lshlrev_b64 v[78:79], 11, v[78:79]
	v_lshl_add_u64 v[78:79], v[66:67], 0, v[78:79]
	s_add_u32 s1, s26, 0x1000
	s_mov_b32 s27, 0
	v_mov_b32_e32 v77, s0
	v_or_b32_e32 v76, s26, v8
	v_lshlrev_b64 v[76:77], 11, v[76:77]
	v_lshl_add_u64 v[76:77], v[66:67], 0, v[76:77]
	global_load_dword v216, v[76:77], off
	s_nop 0
	global_load_dword v217, v[78:79], off
	v_mov_b32_e32 v79, s0
	v_or_b32_e32 v78, s26, v10
	v_lshlrev_b64 v[78:79], 11, v[78:79]
	v_lshl_add_u64 v[78:79], v[66:67], 0, v[78:79]
	v_mov_b32_e32 v77, s0
	v_or_b32_e32 v76, s26, v12
	v_lshlrev_b64 v[76:77], 11, v[76:77]
	v_lshl_add_u64 v[76:77], v[66:67], 0, v[76:77]
	global_load_dword v218, v[76:77], off
	s_nop 0
	global_load_dword v219, v[78:79], off
	v_mov_b32_e32 v79, s0
	v_or_b32_e32 v78, s26, v14
	v_lshlrev_b64 v[78:79], 11, v[78:79]
	v_lshl_add_u64 v[78:79], v[66:67], 0, v[78:79]
	v_mov_b32_e32 v77, s0
	v_or_b32_e32 v76, s26, v16
	v_lshlrev_b64 v[76:77], 11, v[76:77]
	v_lshl_add_u64 v[76:77], v[66:67], 0, v[76:77]
	global_load_dword v220, v[76:77], off
	s_nop 0
	global_load_dword v221, v[78:79], off
	s_addc_u32 s0, s0, 0
	v_mov_b32_e32 v79, s0
	v_or_b32_e32 v78, s1, v18
	v_lshlrev_b64 v[78:79], 11, v[78:79]
	v_lshl_add_u64 v[78:79], v[66:67], 0, v[78:79]
	s_waitcnt vmcnt(0)
	ds_write2st64_b32 v9, v214, v215 offset0:129 offset1:133
	ds_write2st64_b32 v9, v216, v217 offset0:137 offset1:141
	ds_write2st64_b32 v9, v218, v219 offset0:145 offset1:149
	ds_write2st64_b32 v9, v220, v221 offset0:153 offset1:157
	v_mov_b32_e32 v77, s0
	v_or_b32_e32 v76, s1, v20
	v_lshlrev_b64 v[76:77], 11, v[76:77]
	v_lshl_add_u64 v[76:77], v[66:67], 0, v[76:77]
	global_load_dword v214, v[76:77], off
	s_nop 0
	global_load_dword v215, v[78:79], off
	v_mov_b32_e32 v79, s0
	v_or_b32_e32 v78, s1, v22
	v_lshlrev_b64 v[78:79], 11, v[78:79]
	v_lshl_add_u64 v[78:79], v[66:67], 0, v[78:79]
	v_mov_b32_e32 v77, s0
	v_or_b32_e32 v76, s1, v24
	v_lshlrev_b64 v[76:77], 11, v[76:77]
	v_lshl_add_u64 v[76:77], v[66:67], 0, v[76:77]
	global_load_dword v216, v[76:77], off
	s_nop 0
	global_load_dword v217, v[78:79], off
	v_mov_b32_e32 v79, s0
	v_or_b32_e32 v78, s1, v26
	v_lshlrev_b64 v[78:79], 11, v[78:79]
	v_lshl_add_u64 v[78:79], v[66:67], 0, v[78:79]
	v_mov_b32_e32 v77, s0
	v_or_b32_e32 v76, s1, v28
	v_lshlrev_b64 v[76:77], 11, v[76:77]
	v_lshl_add_u64 v[76:77], v[66:67], 0, v[76:77]
	global_load_dword v218, v[76:77], off
	s_nop 0
	global_load_dword v219, v[78:79], off
	v_mov_b32_e32 v79, s0
	v_or_b32_e32 v78, s1, v32
	v_lshlrev_b64 v[78:79], 11, v[78:79]
	v_lshl_add_u64 v[78:79], v[66:67], 0, v[78:79]
	v_mov_b32_e32 v77, s0
	v_or_b32_e32 v76, s1, v30
	v_lshlrev_b64 v[76:77], 11, v[76:77]
	v_lshl_add_u64 v[76:77], v[66:67], 0, v[76:77]
	global_load_dword v220, v[76:77], off
	s_nop 0
	global_load_dword v221, v[78:79], off
	s_waitcnt vmcnt(0)
	ds_write2st64_b32 v9, v214, v215 offset0:161 offset1:165
	ds_write2st64_b32 v9, v216, v217 offset0:169 offset1:173
	ds_write2st64_b32 v9, v218, v219 offset0:177 offset1:181
	ds_write2st64_b32 v9, v220, v221 offset0:185 offset1:189
	s_waitcnt lgkmcnt(0)
	s_barrier
	s_branch .LBB0_487
